# grid barrier leader: release atomic first, then cache invalidate and one wait (safer than leaving the invalidate un-waited)
# speedup vs baseline: 1.0077x; 1.0001x over previous
.LBB0_94:
	s_or_b64 exec, exec, s[0:1]
	s_mov_b64 s[0:1], exec
	v_mbcnt_lo_u32_b32 v0, s0, 0
	v_mbcnt_hi_u32_b32 v0, s1, v0
	v_cmp_eq_u32_e32 vcc, 0, v0
	s_waitcnt vmcnt(0)
	s_and_saveexec_b64 s[4:5], vcc
	s_cbranch_execz .LBB0_96
	s_bcnt1_i32_b64 s0, s[0:1]
	v_mov_b32_e32 v0, 0x2000
	v_mov_b32_e32 v1, s0
	global_atomic_add v0, v1, s[8:9] offset:1024
.LBB0_96:
	s_or_b64 exec, exec, s[4:5]
	buffer_inv sc1
	s_waitcnt vmcnt(0)

.LBB0_836:
	s_or_b64 exec, exec, s[0:1]
	s_mov_b64 s[0:1], exec
	v_mbcnt_lo_u32_b32 v0, s0, 0
	v_mbcnt_hi_u32_b32 v0, s1, v0
	v_cmp_eq_u32_e32 vcc, 0, v0
	s_waitcnt vmcnt(0)
	s_and_saveexec_b64 s[4:5], vcc
	s_cbranch_execz .LBB0_838
	s_bcnt1_i32_b64 s0, s[0:1]
	v_mov_b32_e32 v0, 0x2000
	v_mov_b32_e32 v1, s0
	global_atomic_add v0, v1, s[10:11] offset:1024

.LBB0_1803:
	s_or_b64 exec, exec, s[0:1]
	s_mov_b64 s[0:1], exec
	v_mbcnt_lo_u32_b32 v0, s0, 0
	v_mbcnt_hi_u32_b32 v0, s1, v0
	v_cmp_eq_u32_e32 vcc, 0, v0
	s_waitcnt vmcnt(0)
	s_and_saveexec_b64 s[8:9], vcc
	s_cbranch_execz .LBB0_1805
	s_bcnt1_i32_b64 s0, s[0:1]
	v_mov_b32_e32 v0, 0x2000
	v_mov_b32_e32 v1, s0
	global_atomic_add v0, v1, s[4:5] offset:1024
.LBB0_1805:
	s_or_b64 exec, exec, s[8:9]
	buffer_inv sc1
	s_waitcnt vmcnt(0)
